# adaLN partial sums of layers 1 to 3 moved from the prologue to the idle tails of the layer-0 and layer-1 scores GEMM phases (same code, non-temporal weight loads), their bias+sum reduction at the star
# speedup vs baseline: 1.0983x; 1.0003x over previous
; __device__ __forceinline__ float siluf_(float x) { return x / (1.0f + __expf(-x)); }
; __device__ __forceinline__ void phase_prologue(KP P, const Ctx& c) {
;     ...
;         for (int un = blockIdx.x; un < 4 * 24 * 8; un += gridDim.x) {
;             const int layer = un / 192, r = un % 192, nb = r / 8, kc = r % 8;
;             __syncthreads();
;             for (int i = c.tid; i < 5 * 256; i += 512) { const int v = i >> 8, k = kc * 256 + (i & 255); const float x = v < 4 ? P->in[I_C][v * D + k] : P->in[I_CCTX][k]; sl[i] = siluf_(x); }
;             __syncthreads();
;             const int cg = c.tid & 127, ks = c.tid >> 7;
;             const float* w = P->in[I_ADAW] + ((size_t)layer * D + kc * 256 + ks * 64) * 12288 + nb * 512 + cg * 4;
.LBB0_5:
	s_or_b64 exec, exec, s[4:5]
	s_mov_b64 s[18:19], s[94:95]
	v_mov_b32_e32 v86, v0
	s_load_dword s3, s[94:95], 0x138
	s_load_dwordx2 s[16:17], s[18:19], 0x130
	s_add_u32 s4, s94, 0x138
	s_addc_u32 s5, s95, 0
	v_writelane_b32 v244, s4, 2
	s_waitcnt lgkmcnt(0)
	s_movk_i32 s96, 0x300
	s_cmpk_eq_i32 s3, 0x100
	s_cselect_b32 s96, 0xc0, s96
	s_cmp_lt_i32 s2, s96
	v_readfirstlane_b32 s34, v86
	v_writelane_b32 v244, s5, 3
	s_cbranch_scc0 .LBB0_33
	v_lshlrev_b32_e32 v1, 2, v86
	v_ashrrev_i32_e32 v3, 7, v86
	v_and_b32_e32 v2, 0x1fc, v1
	s_movk_i32 s6, 0x2700
	v_lshlrev_b32_e32 v88, 6, v3
	v_lshl_add_u32 v100, v3, 8, 0
	v_mul_lo_u32 v3, v3, s6
	v_lshlrev_b32_e32 v4, 2, v2
	v_add3_u32 v101, v100, v3, v4
	v_max_i32_e32 v3, 0x800, v86
	v_mov_b32_e32 v91, 0
	v_and_b32_e32 v90, 0x7fc, v1
	v_sub_u32_e32 v3, v3, v86
	s_waitcnt lgkmcnt(0)
	v_lshl_add_u64 v[4:5], s[16:17], 0, v[90:91]
	s_mov_b64 s[8:9], 0x200000
	v_add_u32_e32 v3, 0x1ff, v3
	s_load_dwordx2 s[20:21], s[18:19], 0x20
	v_lshl_add_u64 v[92:93], v[4:5], 0, s[8:9]
	v_lshrrev_b32_e32 v4, 9, v3
	s_movk_i32 s8, 0x1ff
	v_add_u32_e32 v5, 1, v4
	v_cmp_lt_u32_e64 s[8:9], s8, v3
	v_and_b32_e32 v3, 0xfffffe, v5
	v_add_u32_e32 v4, -1, v4
	v_lshl_add_u32 v102, v3, 9, v86
	v_cmp_ne_u32_e64 s[14:15], v5, v3
	v_and_b32_e32 v3, 0x7f, v86
	v_lshrrev_b32_e32 v6, 1, v4
	v_cmp_lt_u32_e64 s[10:11], 1, v4
	v_and_b32_e32 v4, 2, v4
	v_add_u32_e32 v104, 0, v90
	v_lshlrev_b32_e32 v90, 4, v3
	s_movk_i32 s4, 0x500
	s_movk_i32 s6, 0xa00
	v_add_u32_e32 v6, 1, v6
	v_cmp_eq_u32_e64 s[12:13], 0, v4
	v_add_u32_e32 v105, 0, v1
	s_waitcnt lgkmcnt(0)
	v_lshl_add_u64 v[4:5], s[20:21], 0, v[90:91]
	s_mov_b64 s[22:23], 0xb4000
	v_cmp_gt_i32_e64 s[4:5], s4, v86
	v_ashrrev_i32_e32 v89, 31, v88
	v_cmp_gt_i32_e64 s[6:7], s6, v86
	v_add_u32_e32 v87, 0x200, v86
	v_and_b32_e32 v103, -2, v6
	v_lshl_add_u64 v[94:95], v[4:5], 0, s[22:23]
	v_add_u32_e32 v106, 0x1400, v105
	s_movk_i32 s35, 0x2ff
	s_mov_b32 s36, 0xc000
	v_mov_b64_e32 v[96:97], s[20:21]
	v_lshlrev_b32_e32 v90, 2, v2
	s_mov_b32 s37, 0x18000
	s_mov_b32 s40, 0x24000
	s_mov_b32 s41, 0x30000
	s_mov_b32 s43, 0x3c000
	s_mov_b32 s44, 0x48000
	s_mov_b32 s45, 0x54000
	s_mov_b64 s[20:21], 0x60000
	s_movk_i32 s46, 0x7ff
	s_mov_b32 s47, s2
	s_branch .LBB0_8
.LBB0_7:
	s_or_b64 exec, exec, s[26:27]
	s_add_i32 s47, s47, s3
	s_movk_i32 s96, 0x2ff
	s_cmpk_eq_i32 s3, 0x100
	s_cselect_b32 s96, 0xbf, s96
	s_cmp_gt_i32 s47, s96
	s_cbranch_scc1 .LBB0_33

; #define PROBE_REP(bit) for (int _rep = 0; _rep < (((PROBE) >> (bit)) & 1) + 1; ++_rep)
; __device__ __forceinline__ float siluf_(float x) { return x / (1.0f + __expf(-x)); }
; __device__ __forceinline__ KP kp_fresh() { KP p = (KP)__builtin_amdgcn_kernarg_segment_ptr(); asm volatile("" : "+s"(p)); return p; }
; __device__ __forceinline__ void phase_prologue(KP P, const Ctx& c) {
;     ...
;         for (int un = blockIdx.x; un < 4 * 24 * 8; un += gridDim.x) {
;             const int layer = un / 192, r = un % 192, nb = r / 8, kc = r % 8;
;             __syncthreads();
;             for (int i = c.tid; i < 5 * 256; i += 512) { const int v = i >> 8, k = kc * 256 + (i & 255); const float x = v < 4 ? P->in[I_C][v * D + k] : P->in[I_CCTX][k]; sl[i] = siluf_(x); }
;             __syncthreads();
;             const int cg = c.tid & 127, ks = c.tid >> 7;
;             const float* w = P->in[I_ADAW] + ((size_t)layer * D + kc * 256 + ks * 64) * 12288 + nb * 512 + cg * 4;
;             f32x4 a0 = (f32x4){0.f, 0.f, 0.f, 0.f}, a1 = a0, a2 = a0, a3 = a0, a4 = a0;
;             f32x4 wn[8];
; #pragma unroll
;             for (int i = 0; i < 8; ++i) wn[i] = *(const f32x4*)(w + (size_t)i * 12288);
; template <int LAYER, bool LAST> __device__ __forceinline__ void peer_phases(LAS unsigned char* lds, const XcdBarrier& bar) {
;     ...
;     PROBE_REP(2) { KP P = kp_fresh(); unsigned char* ws = P->ws; GPlain g{(const bf16_t*)(ws + WS_H2), (const bf16_t*)(ws + WS_WQ) + (size_t)LAYER * D * D, D, D, D}; EpiF32Plain E{(float*)(ws + WS_S), D}; run_gemm(lds, g, D, E, LAST ? 4 : 0);
;         if (!LAST && _rep == 0) { constexpr int NR = 8 * 16384, SH = (NR + 2) / 3; const int lo = LAYER * SH, hi = (LAYER == 2) ? NR : (LAYER + 1) * SH;
;             if ((int)gridDim.x == 256) { if ((int)blockIdx.x >= 32) peer_convert_rows(kp_fresh(), make_ctx(lds), lo, hi, (int)blockIdx.x - 32, 224); }
;             else peer_convert_rows(kp_fresh(), make_ctx(lds), lo, hi, (int)blockIdx.x, (int)gridDim.x); }
.LBB0_1061:
	v_readlane_b32 s3, v244, 4
	s_cmpk_lg_i32 s3, 0x100
	s_cbranch_scc1 .Lj4a_skip
	s_cmp_lt_u32 s2, 32
	s_cbranch_scc1 .Lj4a_skip
	s_add_i32 s3, s2, 0xa0
	s_cmpk_gt_i32 s3, 0x23f
	s_cbranch_scc1 .Lj4a_skip
	v_writelane_b32 v240, s6, 0
	v_writelane_b32 v240, s7, 1
	v_writelane_b32 v240, s24, 2
	v_writelane_b32 v240, s25, 3
	v_writelane_b32 v240, s26, 4
	v_writelane_b32 v240, s27, 5
	v_writelane_b32 v240, s28, 6
	v_writelane_b32 v240, s29, 7
	v_writelane_b32 v240, s30, 8
	v_writelane_b32 v240, s31, 9
	v_writelane_b32 v240, s35, 10
	v_writelane_b32 v240, s36, 11
	v_writelane_b32 v240, s37, 12
	v_mov_b32_e32 v241, v1
	v_mov_b32_e32 v242, v96
	v_mov_b32_e32 v243, v97
	v_mov_b32_e32 v245, v98
	v_mov_b32_e32 v246, v99
	v_mov_b32_e32 v247, v101
	s_mov_b64 s[18:19], s[94:95]
	s_load_dwordx2 s[16:17], s[18:19], 0x130
	v_mov_b32_e32 v86, v0
	s_movk_i32 s3, 0xe0
	s_waitcnt vmcnt(0) lgkmcnt(0)
	s_barrier
	v_lshlrev_b32_e32 v1, 2, v86
	v_ashrrev_i32_e32 v3, 7, v86
	v_and_b32_e32 v2, 0x1fc, v1
	s_movk_i32 s6, 0x2700
	v_lshlrev_b32_e32 v88, 6, v3
	v_lshl_add_u32 v100, v3, 8, 0
	v_mul_lo_u32 v3, v3, s6
	v_lshlrev_b32_e32 v4, 2, v2
	v_add3_u32 v101, v100, v3, v4
	v_max_i32_e32 v3, 0x800, v86
	v_mov_b32_e32 v91, 0
	v_and_b32_e32 v90, 0x7fc, v1
	v_sub_u32_e32 v3, v3, v86
	s_waitcnt lgkmcnt(0)
	v_lshl_add_u64 v[4:5], s[16:17], 0, v[90:91]
	s_mov_b64 s[8:9], 0x200000
	v_add_u32_e32 v3, 0x1ff, v3
	s_load_dwordx2 s[20:21], s[18:19], 0x20
	v_lshl_add_u64 v[92:93], v[4:5], 0, s[8:9]
	v_lshrrev_b32_e32 v4, 9, v3
	s_movk_i32 s8, 0x1ff
	v_add_u32_e32 v5, 1, v4
	v_cmp_lt_u32_e64 s[8:9], s8, v3
	v_and_b32_e32 v3, 0xfffffe, v5
	v_add_u32_e32 v4, -1, v4
	v_lshl_add_u32 v102, v3, 9, v86
	v_cmp_ne_u32_e64 s[14:15], v5, v3
	v_and_b32_e32 v3, 0x7f, v86
	v_lshrrev_b32_e32 v6, 1, v4
	v_cmp_lt_u32_e64 s[10:11], 1, v4
	v_and_b32_e32 v4, 2, v4
	v_add_u32_e32 v104, 0, v90
	v_lshlrev_b32_e32 v90, 4, v3
	s_movk_i32 s4, 0x500
	s_movk_i32 s6, 0xa00
	v_add_u32_e32 v6, 1, v6
	v_cmp_eq_u32_e64 s[12:13], 0, v4
	v_add_u32_e32 v105, 0, v1
	s_waitcnt lgkmcnt(0)
	v_lshl_add_u64 v[4:5], s[20:21], 0, v[90:91]
	s_mov_b64 s[22:23], 0xb4000
	v_cmp_gt_i32_e64 s[4:5], s4, v86
	v_ashrrev_i32_e32 v89, 31, v88
	v_cmp_gt_i32_e64 s[6:7], s6, v86
	v_add_u32_e32 v87, 0x200, v86
	v_and_b32_e32 v103, -2, v6
	v_lshl_add_u64 v[94:95], v[4:5], 0, s[22:23]
	v_add_u32_e32 v106, 0x1400, v105
	s_movk_i32 s35, 0x2ff
	s_mov_b32 s36, 0xc000
	v_mov_b64_e32 v[96:97], s[20:21]
	v_lshlrev_b32_e32 v90, 2, v2
	s_mov_b32 s37, 0x18000
	s_mov_b32 s40, 0x24000
	s_mov_b32 s41, 0x30000
	s_mov_b32 s43, 0x3c000
	s_mov_b32 s44, 0x48000
	s_mov_b32 s45, 0x54000
	s_mov_b64 s[20:21], 0x60000
	s_movk_i32 s46, 0x7ff
	s_add_i32 s47, s2, 0xa0
	s_branch .Lj4a_8
.Lj4a_7:
	s_or_b64 exec, exec, s[26:27]
	s_add_i32 s47, s47, s3
	s_cmpk_gt_i32 s47, 0x23f
	s_cbranch_scc1 .Lj4a_done

; __device__ __forceinline__ void phase_prologue(KP P, const Ctx& c) {
;     ...
;         }
;         __syncthreads();
.Lj4a_done:
	s_waitcnt vmcnt(0) lgkmcnt(0)
	s_barrier
	v_readlane_b32 s6, v240, 0
	v_readlane_b32 s7, v240, 1
	v_readlane_b32 s24, v240, 2
	v_readlane_b32 s25, v240, 3
	v_readlane_b32 s26, v240, 4
	v_readlane_b32 s27, v240, 5
	v_readlane_b32 s28, v240, 6
	v_readlane_b32 s29, v240, 7
	v_readlane_b32 s30, v240, 8
	v_readlane_b32 s31, v240, 9
	v_readlane_b32 s35, v240, 10
	v_readlane_b32 s36, v240, 11
	v_readlane_b32 s37, v240, 12
	v_mov_b32_e32 v1, v241
	v_mov_b32_e32 v96, v242
	v_mov_b32_e32 v97, v243
	v_mov_b32_e32 v98, v245
	v_mov_b32_e32 v99, v246
	v_mov_b32_e32 v101, v247

; __device__ __forceinline__ void phase_modfin(KP P, const Ctx& c) {
;     for (int i = c.gtid; i < 4 * 5 * 12288; i += c.ngt) { const int n = i % 12288, lv = i / 12288, l = lv / 5, v = lv % 5;
;         float s = P->in[I_ADAB][l * 12288 + n];
;         for (int kc = 0; kc < 8; ++kc) s += ((const float*)(P->ws + WS_MODP))[((size_t)(l * 8 + kc) * 5 + v) * 12288 + n];
;         ((float*)(P->ws + WS_MOD))[i] = s; }
; }
.LBB0_1113:
	s_or_b64 exec, exec, s[38:39]
	s_mov_b64 s[0:1], s[94:95]
	s_waitcnt lgkmcnt(0)
	v_mov_b32_e32 v2, v0
	s_barrier
	v_readlane_b32 s3, v244, 4
	s_cmpk_lg_i32 s3, 0x100
	s_cbranch_scc1 .Lmfa_done
	s_load_dwordx2 s[8:9], s[94:95], 0x28
	s_load_dwordx2 s[10:11], s[94:95], 0x130
	v_lshl_add_u32 v3, s2, 9, v0
	v_add_u32_e32 v3, 0xf000, v3
	v_mov_b32_e32 v4, 0x2d000
	v_cmp_lt_u32_e64 s[14:15], v3, v4
	s_and_saveexec_b64 s[12:13], s[14:15]
	s_cbranch_execz .Lmfa_end
	v_lshrrev_b32_e32 v4, 12, v3
	v_mul_u32_u24_e32 v4, 0xaaab, v4
	v_lshrrev_b32_e32 v4, 17, v4
	v_mul_u32_u24_e32 v5, 0x3000, v4
	v_sub_u32_e32 v5, v3, v5
	v_mul_u32_u24_e32 v6, 0x3334, v4
	v_lshrrev_b32_e32 v6, 16, v6
	v_mul_u32_u24_e32 v7, 5, v6
	v_sub_u32_e32 v7, v4, v7
	v_mul_u32_u24_e32 v8, 0x3000, v6
	v_add_lshl_u32 v8, v8, v5, 2
	v_mul_u32_u24_e32 v9, 40, v6
	v_add_u32_e32 v9, v9, v7
	v_mul_u32_u24_e32 v9, 0x3000, v9
	v_add_lshl_u32 v9, v9, v5, 2
	v_add_u32_e32 v9, 0x200000, v9
	v_lshlrev_b32_e32 v10, 2, v3
	v_add_u32_e32 v10, 0xa00000, v10
	s_waitcnt lgkmcnt(0)
	global_load_dword v11, v8, s[8:9]
	global_load_dword v12, v9, s[10:11]
	v_add_u32_e32 v9, 0x3c000, v9
	global_load_dword v13, v9, s[10:11]
	v_add_u32_e32 v9, 0x3c000, v9
	global_load_dword v14, v9, s[10:11]
	v_add_u32_e32 v9, 0x3c000, v9
	global_load_dword v15, v9, s[10:11]
	v_add_u32_e32 v9, 0x3c000, v9
	global_load_dword v16, v9, s[10:11]
	v_add_u32_e32 v9, 0x3c000, v9
	global_load_dword v17, v9, s[10:11]
	v_add_u32_e32 v9, 0x3c000, v9
	global_load_dword v18, v9, s[10:11]
	v_add_u32_e32 v9, 0x3c000, v9
	global_load_dword v19, v9, s[10:11]
	s_waitcnt vmcnt(7)
	v_add_f32_e32 v11, v11, v12
	s_waitcnt vmcnt(6)
	v_add_f32_e32 v11, v11, v13
	s_waitcnt vmcnt(5)
	v_add_f32_e32 v11, v11, v14
	s_waitcnt vmcnt(4)
	v_add_f32_e32 v11, v11, v15
	s_waitcnt vmcnt(3)
	v_add_f32_e32 v11, v11, v16
	s_waitcnt vmcnt(2)
	v_add_f32_e32 v11, v11, v17
	s_waitcnt vmcnt(1)
	v_add_f32_e32 v11, v11, v18
	s_waitcnt vmcnt(0)
	v_add_f32_e32 v11, v11, v19
	global_store_dword v10, v11, s[10:11]

; #define SEL_LOAD(k) do { const int pid_ = 2 * row_lo + c.gw + (k) * c.ngw; const float* sp_ = S + (size_t)(pid_ >> 1) * D + (2 * (pid_ & 1)) * 512 + lane * 8; \
;         sn[0][0] = *(const f32x4*)sp_; sn[0][1] = *(const f32x4*)(sp_ + 4); sn[1][0] = *(const f32x4*)(sp_ + 512); sn[1][1] = *(const f32x4*)(sp_ + 516); } while (0)
; __device__ __forceinline__ void phase_peer_select(KP P, const Ctx& c, int row_lo) {
;     const float* S = (const float*)(P->ws + WS_S); float* SW = (float*)(P->ws + WS_SELW);
;     constexpr int KMIN = (int)0x80000000;
;     const int nps = (2 * (T - row_lo) - c.gw + c.ngw - 1) / c.ngw;
;     f32x4 sn[2][2];
;     ...
;     { int lane = c.lane; asm volatile("" : "+v"(lane)); if (nps > 0) SEL_LOAD(0); }
.Lmfa_done:
	s_load_dwordx2 s[40:41], s[0:1], 0x130
	v_readfirstlane_b32 s0, v2
	s_ashr_i32 s0, s0, 6
	v_readlane_b32 s1, v239, 11
	s_add_i32 s4, s62, 0x87ff
	s_add_i32 s3, s0, s1
	s_waitcnt lgkmcnt(0)
	s_add_u32 s1, s40, 0x45400000
	s_addc_u32 s8, s41, 0
	s_abs_i32 s12, s62
	v_cvt_f32_u32_e32 v3, s12
	v_and_b32_e32 v34, 63, v2
	s_sub_i32 s9, 0, s12
	v_writelane_b32 v239, s4, 27
	v_rcp_iflag_f32_e32 v2, v3
	s_ashr_i32 s63, s62, 31
	s_sub_i32 s4, s4, s3
	v_writelane_b32 v239, s62, 28
	v_mul_f32_e32 v2, 0x4f7ffffe, v2
	v_cvt_u32_f32_e32 v2, v2
	s_ashr_i32 s5, s4, 31
	v_writelane_b32 v239, s63, 29
	s_abs_i32 s4, s4
	v_readfirstlane_b32 s10, v2
	s_mul_i32 s9, s9, s10
	s_mul_hi_u32 s9, s10, s9
	s_add_i32 s9, s10, s9
	v_writelane_b32 v239, s9, 30
	s_mul_hi_u32 s9, s4, s9
	s_mul_i32 s10, s9, s12
	s_sub_i32 s4, s4, s10
	s_xor_b32 s5, s5, s63
	s_add_i32 s10, s9, 1
	s_sub_i32 s11, s4, s12
	s_cmp_ge_u32 s4, s12
	s_cselect_b32 s9, s10, s9
	s_cselect_b32 s4, s11, s4
	s_add_i32 s10, s9, 1
	s_cmp_ge_u32 s4, s12
	s_cselect_b32 s4, s10, s9
	s_xor_b32 s4, s4, s5
	s_sub_i32 s4, s4, s5
	s_cmp_gt_i32 s4, 0
	v_mov_b32_e32 v2, v34
	s_cselect_b64 s[38:39], -1, 0
	s_cmp_lt_i32 s4, 1
	v_writelane_b32 v239, s12, 31
	s_cbranch_scc1 .LBB0_1115
	s_ashr_i32 s10, s3, 1
	s_ashr_i32 s11, s10, 31
	s_lshl_b64 s[10:11], s[10:11], 13
	s_add_u32 s5, s1, s10
	s_addc_u32 s9, s8, s11
	s_lshl_b32 s10, s0, 12
	s_and_b32 s10, s10, 0x1000
	s_add_u32 s10, s5, s10
	v_lshlrev_b32_e32 v2, 3, v2
	s_addc_u32 s11, s9, 0
	v_ashrrev_i32_e32 v3, 31, v2
	v_lshl_add_u64 v[2:3], v[2:3], 2, s[10:11]
	global_load_dwordx4 v[26:29], v[2:3], off offset:16
	global_load_dwordx4 v[30:33], v[2:3], off
	global_load_dwordx4 v[18:21], v[2:3], off offset:2064
	global_load_dwordx4 v[22:25], v[2:3], off offset:2048
	s_andn2_b64 vcc, exec, s[38:39]
	s_cbranch_vccz .LBB0_1116
	s_branch .LBB0_1180

; #define PROBE_REP(bit) for (int _rep = 0; _rep < (((PROBE) >> (bit)) & 1) + 1; ++_rep)
; __device__ __forceinline__ float siluf_(float x) { return x / (1.0f + __expf(-x)); }
; __device__ __forceinline__ KP kp_fresh() { KP p = (KP)__builtin_amdgcn_kernarg_segment_ptr(); asm volatile("" : "+s"(p)); return p; }
; __device__ __forceinline__ void phase_prologue(KP P, const Ctx& c) {
;     ...
;         for (int un = blockIdx.x; un < 4 * 24 * 8; un += gridDim.x) {
;             const int layer = un / 192, r = un % 192, nb = r / 8, kc = r % 8;
;             __syncthreads();
;             for (int i = c.tid; i < 5 * 256; i += 512) { const int v = i >> 8, k = kc * 256 + (i & 255); const float x = v < 4 ? P->in[I_C][v * D + k] : P->in[I_CCTX][k]; sl[i] = siluf_(x); }
;             __syncthreads();
;             const int cg = c.tid & 127, ks = c.tid >> 7;
;             const float* w = P->in[I_ADAW] + ((size_t)layer * D + kc * 256 + ks * 64) * 12288 + nb * 512 + cg * 4;
;             f32x4 a0 = (f32x4){0.f, 0.f, 0.f, 0.f}, a1 = a0, a2 = a0, a3 = a0, a4 = a0;
;             f32x4 wn[8];
; #pragma unroll
;             for (int i = 0; i < 8; ++i) wn[i] = *(const f32x4*)(w + (size_t)i * 12288);
; template <int LAYER, bool LAST> __device__ __forceinline__ void peer_phases(LAS unsigned char* lds, const XcdBarrier& bar) {
;     ...
;     PROBE_REP(2) { KP P = kp_fresh(); unsigned char* ws = P->ws; GPlain g{(const bf16_t*)(ws + WS_H2), (const bf16_t*)(ws + WS_WQ) + (size_t)LAYER * D * D, D, D, D}; EpiF32Plain E{(float*)(ws + WS_S), D}; run_gemm(lds, g, D, E, LAST ? 4 : 0);
;         if (!LAST && _rep == 0) { constexpr int NR = 8 * 16384, SH = (NR + 2) / 3; const int lo = LAYER * SH, hi = (LAYER == 2) ? NR : (LAYER + 1) * SH;
;             if ((int)gridDim.x == 256) { if ((int)blockIdx.x >= 32) peer_convert_rows(kp_fresh(), make_ctx(lds), lo, hi, (int)blockIdx.x - 32, 224); }
;             else peer_convert_rows(kp_fresh(), make_ctx(lds), lo, hi, (int)blockIdx.x, (int)gridDim.x); }
.LBB0_2043:
	v_readlane_b32 s3, v244, 4
	s_cmpk_lg_i32 s3, 0x100
	s_cbranch_scc1 .Lj4b_skip
	s_cmp_lt_u32 s2, 32
	s_cbranch_scc1 .Lj4b_skip
	s_add_i32 s3, s2, 0x220
	s_cmpk_gt_i32 s3, 0x2ff
	s_cbranch_scc1 .Lj4b_skip
	v_writelane_b32 v240, s6, 0
	v_writelane_b32 v240, s7, 1
	v_writelane_b32 v240, s24, 2
	v_writelane_b32 v240, s25, 3
	v_writelane_b32 v240, s26, 4
	v_writelane_b32 v240, s27, 5
	v_writelane_b32 v240, s28, 6
	v_writelane_b32 v240, s29, 7
	v_writelane_b32 v240, s30, 8
	v_writelane_b32 v240, s31, 9
	v_writelane_b32 v240, s35, 10
	v_writelane_b32 v240, s36, 11
	v_writelane_b32 v240, s37, 12
	v_mov_b32_e32 v241, v1
	s_mov_b64 s[18:19], s[94:95]
	s_load_dwordx2 s[16:17], s[18:19], 0x130
	v_mov_b32_e32 v86, v0
	s_movk_i32 s3, 0xe0
	s_waitcnt vmcnt(0) lgkmcnt(0)
	s_barrier
	v_lshlrev_b32_e32 v1, 2, v86
	v_ashrrev_i32_e32 v3, 7, v86
	v_and_b32_e32 v2, 0x1fc, v1
	s_movk_i32 s6, 0x2700
	v_lshlrev_b32_e32 v88, 6, v3
	v_lshl_add_u32 v100, v3, 8, 0
	v_mul_lo_u32 v3, v3, s6
	v_lshlrev_b32_e32 v4, 2, v2
	v_add3_u32 v101, v100, v3, v4
	v_max_i32_e32 v3, 0x800, v86
	v_mov_b32_e32 v91, 0
	v_and_b32_e32 v90, 0x7fc, v1
	v_sub_u32_e32 v3, v3, v86
	s_waitcnt lgkmcnt(0)
	v_lshl_add_u64 v[4:5], s[16:17], 0, v[90:91]
	s_mov_b64 s[8:9], 0x200000
	v_add_u32_e32 v3, 0x1ff, v3
	s_load_dwordx2 s[20:21], s[18:19], 0x20
	v_lshl_add_u64 v[92:93], v[4:5], 0, s[8:9]
	v_lshrrev_b32_e32 v4, 9, v3
	s_movk_i32 s8, 0x1ff
	v_add_u32_e32 v5, 1, v4
	v_cmp_lt_u32_e64 s[8:9], s8, v3
	v_and_b32_e32 v3, 0xfffffe, v5
	v_add_u32_e32 v4, -1, v4
	v_lshl_add_u32 v102, v3, 9, v86
	v_cmp_ne_u32_e64 s[14:15], v5, v3
	v_and_b32_e32 v3, 0x7f, v86
	v_lshrrev_b32_e32 v6, 1, v4
	v_cmp_lt_u32_e64 s[10:11], 1, v4
	v_and_b32_e32 v4, 2, v4
	v_add_u32_e32 v104, 0, v90
	v_lshlrev_b32_e32 v90, 4, v3
	s_movk_i32 s4, 0x500
	s_movk_i32 s6, 0xa00
	v_add_u32_e32 v6, 1, v6
	v_cmp_eq_u32_e64 s[12:13], 0, v4
	v_add_u32_e32 v105, 0, v1
	s_waitcnt lgkmcnt(0)
	v_lshl_add_u64 v[4:5], s[20:21], 0, v[90:91]
	s_mov_b64 s[22:23], 0xb4000
	v_cmp_gt_i32_e64 s[4:5], s4, v86
	v_ashrrev_i32_e32 v89, 31, v88
	v_cmp_gt_i32_e64 s[6:7], s6, v86
	v_add_u32_e32 v87, 0x200, v86
	v_and_b32_e32 v103, -2, v6
	v_lshl_add_u64 v[94:95], v[4:5], 0, s[22:23]
	v_add_u32_e32 v106, 0x1400, v105
	s_movk_i32 s35, 0x2ff
	s_mov_b32 s36, 0xc000
	v_mov_b64_e32 v[96:97], s[20:21]
	v_lshlrev_b32_e32 v90, 2, v2
	s_mov_b32 s37, 0x18000
	s_mov_b32 s40, 0x24000
	s_mov_b32 s41, 0x30000
	s_mov_b32 s43, 0x3c000
	s_mov_b32 s44, 0x48000
	s_mov_b32 s45, 0x54000
	s_mov_b64 s[20:21], 0x60000
	s_movk_i32 s46, 0x7ff
	s_add_i32 s47, s2, 0x220
	s_branch .Lj4b_8

; __device__ __forceinline__ void phase_prologue(KP P, const Ctx& c) {
;     ...
;         }
;         __syncthreads();
.Lj4b_done:
	s_waitcnt vmcnt(0) lgkmcnt(0)
	s_barrier
	v_readlane_b32 s6, v240, 0
	v_readlane_b32 s7, v240, 1
	v_readlane_b32 s24, v240, 2
	v_readlane_b32 s25, v240, 3
	v_readlane_b32 s26, v240, 4
	v_readlane_b32 s27, v240, 5
	v_readlane_b32 s28, v240, 6
	v_readlane_b32 s29, v240, 7
	v_readlane_b32 s30, v240, 8
	v_readlane_b32 s31, v240, 9
	v_readlane_b32 s35, v240, 10
	v_readlane_b32 s36, v240, 11
	v_readlane_b32 s37, v240, 12
	v_mov_b32_e32 v1, v241

; __device__ __forceinline__ void phase_modfin(KP P, const Ctx& c) {
;     for (int i = c.gtid; i < 4 * 5 * 12288; i += c.ngt) { const int n = i % 12288, lv = i / 12288, l = lv / 5, v = lv % 5;
;         float s = P->in[I_ADAB][l * 12288 + n];
;         for (int kc = 0; kc < 8; ++kc) s += ((const float*)(P->ws + WS_MODP))[((size_t)(l * 8 + kc) * 5 + v) * 12288 + n];
;         ((float*)(P->ws + WS_MOD))[i] = s; }
; }
.LBB0_2095:
	s_or_b64 exec, exec, s[38:39]
	s_mov_b64 s[0:1], s[94:95]
	s_waitcnt lgkmcnt(0)
	v_mov_b32_e32 v2, v0
	s_barrier
	v_readlane_b32 s3, v244, 4
	s_cmpk_lg_i32 s3, 0x100
	s_cbranch_scc1 .Lmfb_done
	s_load_dwordx2 s[8:9], s[94:95], 0x28
	s_load_dwordx2 s[10:11], s[94:95], 0x130
	v_lshl_add_u32 v3, s2, 9, v0
	v_add_u32_e32 v3, 0x2d000, v3
	v_mov_b32_e32 v4, 0x3c000
	v_cmp_lt_u32_e64 s[14:15], v3, v4
	s_and_saveexec_b64 s[12:13], s[14:15]
	s_cbranch_execz .Lmfb_end
	v_lshrrev_b32_e32 v4, 12, v3
	v_mul_u32_u24_e32 v4, 0xaaab, v4
	v_lshrrev_b32_e32 v4, 17, v4
	v_mul_u32_u24_e32 v5, 0x3000, v4
	v_sub_u32_e32 v5, v3, v5
	v_mul_u32_u24_e32 v6, 0x3334, v4
	v_lshrrev_b32_e32 v6, 16, v6
	v_mul_u32_u24_e32 v7, 5, v6
	v_sub_u32_e32 v7, v4, v7
	v_mul_u32_u24_e32 v8, 0x3000, v6
	v_add_lshl_u32 v8, v8, v5, 2
	v_mul_u32_u24_e32 v9, 40, v6
	v_add_u32_e32 v9, v9, v7
	v_mul_u32_u24_e32 v9, 0x3000, v9
	v_add_lshl_u32 v9, v9, v5, 2
	v_add_u32_e32 v9, 0x200000, v9
	v_lshlrev_b32_e32 v10, 2, v3
	v_add_u32_e32 v10, 0xa00000, v10
	s_waitcnt lgkmcnt(0)
	global_load_dword v11, v8, s[8:9]
	global_load_dword v12, v9, s[10:11]
	v_add_u32_e32 v9, 0x3c000, v9
	global_load_dword v13, v9, s[10:11]
	v_add_u32_e32 v9, 0x3c000, v9
	global_load_dword v14, v9, s[10:11]
	v_add_u32_e32 v9, 0x3c000, v9
	global_load_dword v15, v9, s[10:11]
	v_add_u32_e32 v9, 0x3c000, v9
	global_load_dword v16, v9, s[10:11]
	v_add_u32_e32 v9, 0x3c000, v9
	global_load_dword v17, v9, s[10:11]
	v_add_u32_e32 v9, 0x3c000, v9
	global_load_dword v18, v9, s[10:11]
	v_add_u32_e32 v9, 0x3c000, v9
	global_load_dword v19, v9, s[10:11]
	s_waitcnt vmcnt(7)
	v_add_f32_e32 v11, v11, v12
	s_waitcnt vmcnt(6)
	v_add_f32_e32 v11, v11, v13
	s_waitcnt vmcnt(5)
	v_add_f32_e32 v11, v11, v14
	s_waitcnt vmcnt(4)
	v_add_f32_e32 v11, v11, v15
	s_waitcnt vmcnt(3)
	v_add_f32_e32 v11, v11, v16
	s_waitcnt vmcnt(2)
	v_add_f32_e32 v11, v11, v17
	s_waitcnt vmcnt(1)
	v_add_f32_e32 v11, v11, v18
	s_waitcnt vmcnt(0)
	v_add_f32_e32 v11, v11, v19
	global_store_dword v10, v11, s[10:11]

; #define SEL_LOAD(k) do { const int pid_ = 2 * row_lo + c.gw + (k) * c.ngw; const float* sp_ = S + (size_t)(pid_ >> 1) * D + (2 * (pid_ & 1)) * 512 + lane * 8; \
;         sn[0][0] = *(const f32x4*)sp_; sn[0][1] = *(const f32x4*)(sp_ + 4); sn[1][0] = *(const f32x4*)(sp_ + 512); sn[1][1] = *(const f32x4*)(sp_ + 516); } while (0)
; __device__ __forceinline__ void phase_peer_select(KP P, const Ctx& c, int row_lo) {
;     const float* S = (const float*)(P->ws + WS_S); float* SW = (float*)(P->ws + WS_SELW);
;     constexpr int KMIN = (int)0x80000000;
;     const int nps = (2 * (T - row_lo) - c.gw + c.ngw - 1) / c.ngw;
;     f32x4 sn[2][2];
;     ...
;     { int lane = c.lane; asm volatile("" : "+v"(lane)); if (nps > 0) SEL_LOAD(0); }
.Lmfb_done:
	s_load_dwordx2 s[40:41], s[0:1], 0x130
	v_readfirstlane_b32 s0, v2
	s_ashr_i32 s0, s0, 6
	v_readlane_b32 s1, v239, 11
	s_add_i32 s3, s0, s1
	s_waitcnt lgkmcnt(0)
	s_add_u32 s1, s40, 0x45400000
	v_readlane_b32 s4, v239, 27
	s_addc_u32 s8, s41, 0
	s_sub_i32 s4, s4, s3
	s_ashr_i32 s5, s4, 31
	s_abs_i32 s4, s4
	v_readlane_b32 s9, v239, 30
	v_readlane_b32 s10, v239, 28
	s_mul_hi_u32 s9, s4, s9
	v_readlane_b32 s12, v239, 31
	s_mul_i32 s10, s9, s12
	v_readlane_b32 s11, v239, 29
	s_sub_i32 s4, s4, s10
	s_xor_b32 s5, s5, s11
	s_add_i32 s10, s9, 1
	s_sub_i32 s11, s4, s12
	s_cmp_ge_u32 s4, s12
	s_cselect_b32 s9, s10, s9
	s_cselect_b32 s4, s11, s4
	s_add_i32 s10, s9, 1
	s_cmp_ge_u32 s4, s12
	s_cselect_b32 s4, s10, s9
	s_xor_b32 s4, s4, s5
	s_sub_i32 s4, s4, s5
	v_and_b32_e32 v34, 63, v2
	s_cmp_gt_i32 s4, 0
	v_mov_b32_e32 v2, v34
	s_cselect_b64 s[38:39], -1, 0
	s_cmp_lt_i32 s4, 1
	s_cbranch_scc1 .LBB0_2097
	s_ashr_i32 s10, s3, 1
	s_ashr_i32 s11, s10, 31
	s_lshl_b64 s[10:11], s[10:11], 13
	s_add_u32 s5, s1, s10
	s_addc_u32 s9, s8, s11
	s_lshl_b32 s10, s0, 12
	s_and_b32 s10, s10, 0x1000
	s_add_u32 s10, s5, s10
	v_lshlrev_b32_e32 v2, 3, v2
	s_addc_u32 s11, s9, 0
	v_ashrrev_i32_e32 v3, 31, v2
	v_lshl_add_u64 v[2:3], v[2:3], 2, s[10:11]
	global_load_dwordx4 v[26:29], v[2:3], off offset:16
	global_load_dwordx4 v[30:33], v[2:3], off
	global_load_dwordx4 v[18:21], v[2:3], off offset:2064
	global_load_dwordx4 v[22:25], v[2:3], off offset:2048
	s_andn2_b64 vcc, exec, s[38:39]
	s_cbranch_vccz .LBB0_2098
	s_branch .LBB0_2162
